# all individually-validated latency trims combined on v63: XCD-local scan->core (+core unit remap), ret_scan counted wait, early invalidate, LN staging under row loads, gate-epilogue PP touch
# baseline (speedup 1.0000x reference)
.LBB0_1741:
	v_readlane_b32 s0, v253, 37
	v_readlane_b32 s16, v250, 0
	s_or_b32 s0, s0, 4
	v_readlane_b32 s19, v250, 3
	s_cmp_ge_i32 s0, s19
	v_readlane_b32 s17, v250, 1
	v_readlane_b32 s18, v250, 2
	s_cbranch_scc1 .LBB0_1797
	s_waitcnt vmcnt(0)
	v_readlane_b32 s2, v253, 40
	v_readlane_b32 s3, v253, 41
	s_and_b64 vcc, exec, s[2:3]
	s_waitcnt vmcnt(0)
	s_barrier
	s_cbranch_vccnz .LBB0_1796
	s_mov_b32 s2, -1
	s_nop 0
	v_mbcnt_lo_u32_b32 v0, s2, 0
	v_mbcnt_hi_u32_b32 v0, s2, v0
	s_nop 0
	v_cmp_eq_u32_e32 vcc, 0, v0
	s_and_saveexec_b64 s[16:17], vcc
	s_cbranch_execz .LBB0_1795
	s_cmp_lg_u32 s101, 1
	s_cbranch_scc1 .Lmy_gfull_9
	v_readlane_b32 s100, v253, 37
	v_readlane_b32 s3, v250, 7
	v_readlane_b32 s8, v250, 0
	v_readlane_b32 s9, v250, 1
	s_lshl_b32 s12, s100, 12
	s_add_i32 s12, s12, 0x9000
	s_and_b32 s13, s3, 63
	s_lshl_b32 s13, s13, 6
	s_add_i32 s2, s12, s13
	s_add_u32 s8, s8, 0x70000
	s_addc_u32 s9, s9, 0
	v_mov_b32_e32 v0, s2
	v_mov_b32_e32 v1, 1
	s_waitcnt vmcnt(0) lgkmcnt(0)
	global_atomic_add v0, v1, s[8:9]
	buffer_inv sc1
	s_mov_b32 exec_lo, 0xff
	s_mov_b32 exec_hi, 0
	s_mov_b32 s2, -1
	v_mbcnt_lo_u32_b32 v0, s2, 0
	v_mbcnt_hi_u32_b32 v0, s2, v0
	v_lshlrev_b32_e32 v0, 9, v0
	s_and_b32 s13, s3, 7
	s_lshl_b32 s13, s13, 6
	s_add_i32 s13, s13, s12
	v_add_u32_e32 v0, s13, v0
	s_mov_b32 s100, 0

.Lmy_g9_done:
	s_mov_b64 exec, 1
	s_branch .LBB0_1795
.Lmy_gfull_9:
	v_readlane_b32 s2, v252, 30
	s_waitcnt vmcnt(0) expcnt(0) lgkmcnt(0)
	s_nop 0
	v_mov_b32_e32 v0, s2
	ds_read_b32 v2, v0
	v_readlane_b32 s2, v252, 31
	s_waitcnt lgkmcnt(0)
	v_cmp_ne_u32_e32 vcc, 0, v2
	v_mov_b32_e32 v0, s2
	ds_read_b32 v0, v0
	s_cbranch_vccnz .LBB0_1759
	v_readlane_b32 s8, v250, 4
	v_readlane_b32 s9, v250, 5
	s_load_dwordx2 s[2:3], s[8:9], 0x4
	s_waitcnt lgkmcnt(0)
	s_mul_i32 s2, s2, s94
	s_mul_i32 s2, s2, s3
	s_mov_b32 s3, 1
	s_branch .LBB0_1747
